# prompt attention softmax: running max only advanced (and accumulators rescaled) when a row max grows by more than 8 in the log2 domain; exact reformulation, same bf16 P / f32 accumulate
# speedup vs baseline: 1.0389x; 1.0311x over previous
; #define MFMA32(a, b, c) __builtin_amdgcn_mfma_f32_32x32x16_bf16((a), (b), (c), 0, 0, 0)
; DI float xhalf_max(float v) { const auto r = __builtin_amdgcn_permlane32_swap(__float_as_uint(v), __float_as_uint(v), false, false); return fmaxf(__uint_as_float(r[0]), __uint_as_float(r[1])); }
;     ...
; #pragma unroll
;         for (int ks = 0; ks < NKS; ++ks) { const bf16x8 a0 = *(const bf16x8*)(Kt + lr * KSTR + 16 * ks + 8 * hi), a1 = *(const bf16x8*)(Kt + (32 + lr) * KSTR + 16 * ks + 8 * hi);
;             bf16x8 qq;
;             if (QREG == 1) qq = qf[ks];
;             else if (QREG == 2) qq = 16 * ks < DN ? qf[ks < NQF ? ks : 0] : *(const bf16x8*)(qr_row + (16 * ks - DN) + 8 * hi);
;             else qq = 16 * ks < DN ? *(const bf16x8*)(qa_row + 16 * ks + 8 * hi) : qf[(16 * ks - DN) / 16 < NQF ? (16 * ks - DN) / 16 : 0];
;             s0 = MFMA32(a0, qq, s0); s1 = MFMA32(a1, qq, s1);
;             if ((ks & 3) == 3) __builtin_amdgcn_sched_barrier(0); }
;         if (t == 0) {
; #pragma unroll
;             for (int i = 0; i < 16; ++i) { if (i >= 8) s0[i] = -INFINITY; s1[i] = -INFINITY; } }
;         float mx = s0[0];
; #pragma unroll
;         for (int i = 1; i < 16; ++i) mx = fmaxf(mx, s0[i]);
; #pragma unroll
;         for (int i = 0; i < 16; ++i) mx = fmaxf(mx, s1[i]);
;         mx = xhalf_max(mx);
;         const float mnew = fmaxf(mrun, mx), alpha = __builtin_amdgcn_exp2f(mrun - mnew);
;         const bool resc = __builtin_amdgcn_ballot_w64(mnew != mrun) != 0ull; mrun = mnew;
;         float ps = 0.f;
; #pragma unroll
;         for (int i = 0; i < 16; ++i) { s0[i] = __builtin_amdgcn_exp2f(s0[i] - mnew); s1[i] = __builtin_amdgcn_exp2f(s1[i] - mnew); ps += s0[i] + s1[i]; }
;         lrun = lrun * alpha + ps;
;         if (resc) {
; #pragma unroll
;             for (int d = 0; d < 4; ++d)
; #pragma unroll
;                 for (int i = 0; i < 16; ++i) oacc[d][i] *= alpha; }
.LBB0_1910:
	s_mul_i32 s17, s17, 0xa800
	s_add_i32 s0, s17, 0
	v_lshlrev_b32_e32 v0, 1, v186
	v_add3_u32 v0, s0, v189, v0
	ds_read_b128 v[2:5], v0
	ds_read_b128 v[6:9], v0 offset:12800
	ds_read_b128 v[10:13], v0 offset:32
	ds_read_b128 v[226:229], v0 offset:12832
	ds_read_b128 v[230:233], v0 offset:64
	ds_read_b128 v[238:241], v0 offset:12864
	v_add3_u32 v225, s0, v14, v222
	v_add_u32_e32 v225, 0x6400, v225
	v_add_u32_e32 v234, 0x1100, v225
	v_add_u32_e32 v235, 0x2200, v225
	v_add_u32_e32 v236, 0x3300, v225
	s_waitcnt lgkmcnt(5)
	v_mfma_f32_32x32x16_bf16 v[80:95], v[2:5], v[112:115], 0
	ds_read_b128 v[2:5], v0 offset:96
	s_waitcnt lgkmcnt(5)
	v_mfma_f32_32x32x16_bf16 v[96:111], v[6:9], v[112:115], 0
	ds_read_b128 v[6:9], v0 offset:12896
	s_waitcnt lgkmcnt(5)
	v_mfma_f32_32x32x16_bf16 v[80:95], v[10:13], v[116:119], v[80:95]
	ds_read_b128 v[10:13], v0 offset:128
	s_waitcnt lgkmcnt(5)
	v_mfma_f32_32x32x16_bf16 v[96:111], v[226:229], v[116:119], v[96:111]
	ds_read_b128 v[226:229], v0 offset:12928
	s_waitcnt lgkmcnt(5)
	v_mfma_f32_32x32x16_bf16 v[80:95], v[230:233], v[120:123], v[80:95]
	ds_read_b128 v[230:233], v0 offset:160
	s_waitcnt lgkmcnt(5)
	v_mfma_f32_32x32x16_bf16 v[96:111], v[238:241], v[120:123], v[96:111]
	ds_read_b128 v[238:241], v0 offset:12960
	s_waitcnt lgkmcnt(5)
	v_mfma_f32_32x32x16_bf16 v[80:95], v[2:5], v[124:127], v[80:95]
	ds_read_b128 v[2:5], v0 offset:192
	s_waitcnt lgkmcnt(5)
	v_mfma_f32_32x32x16_bf16 v[96:111], v[6:9], v[124:127], v[96:111]
	ds_read_b128 v[6:9], v0 offset:12992
	s_waitcnt lgkmcnt(5)
	v_mfma_f32_32x32x16_bf16 v[80:95], v[10:13], v[128:131], v[80:95]
	ds_read_b128 v[10:13], v0 offset:224
	s_waitcnt lgkmcnt(5)
	v_mfma_f32_32x32x16_bf16 v[96:111], v[226:229], v[128:131], v[96:111]
	ds_read_b128 v[226:229], v0 offset:13024
	s_waitcnt lgkmcnt(5)
	v_mfma_f32_32x32x16_bf16 v[80:95], v[230:233], v[132:135], v[80:95]
	ds_read_b128 v[230:233], v0 offset:256
	s_waitcnt lgkmcnt(5)
	v_mfma_f32_32x32x16_bf16 v[96:111], v[238:241], v[132:135], v[96:111]
	ds_read_b128 v[238:241], v0 offset:13056
	s_waitcnt lgkmcnt(5)
	v_mfma_f32_32x32x16_bf16 v[80:95], v[2:5], v[136:139], v[80:95]
	ds_read_b128 v[2:5], v0 offset:288
	s_waitcnt lgkmcnt(5)
	v_mfma_f32_32x32x16_bf16 v[96:111], v[6:9], v[136:139], v[96:111]
	ds_read_b128 v[6:9], v0 offset:13088
	s_waitcnt lgkmcnt(5)
	v_mfma_f32_32x32x16_bf16 v[80:95], v[10:13], v[140:143], v[80:95]
	ds_read_b128 v[10:13], v0 offset:320
	s_waitcnt lgkmcnt(5)
	v_mfma_f32_32x32x16_bf16 v[96:111], v[226:229], v[140:143], v[96:111]
	ds_read_b128 v[226:229], v0 offset:13120
	s_waitcnt lgkmcnt(5)
	v_mfma_f32_32x32x16_bf16 v[80:95], v[230:233], v[144:147], v[80:95]
	ds_read_b128 v[230:233], v0 offset:352
	s_waitcnt lgkmcnt(5)
	v_mfma_f32_32x32x16_bf16 v[96:111], v[238:241], v[144:147], v[96:111]
	ds_read_b128 v[238:241], v0 offset:13152
	s_waitcnt lgkmcnt(5)
	v_mfma_f32_32x32x16_bf16 v[80:95], v[2:5], v[148:151], v[80:95]
	ds_read2_b64 v[242:245], v225 offset1:2
	s_waitcnt lgkmcnt(5)
	v_mfma_f32_32x32x16_bf16 v[96:111], v[6:9], v[148:151], v[96:111]
	s_waitcnt lgkmcnt(4)
	v_mfma_f32_32x32x16_bf16 v[80:95], v[10:13], v[152:155], v[80:95]
	s_waitcnt lgkmcnt(3)
	v_mfma_f32_32x32x16_bf16 v[96:111], v[226:229], v[152:155], v[96:111]
	ds_read2_b64 v[226:229], v225 offset0:4 offset1:6
	s_waitcnt lgkmcnt(3)
	v_mfma_f32_32x32x16_bf16 v[80:95], v[230:233], v[156:159], v[80:95]
	ds_read2_b64 v[230:233], v225 offset0:8 offset1:10
	s_waitcnt lgkmcnt(3)
	v_mfma_f32_32x32x16_bf16 v[96:111], v[238:241], v[156:159], v[96:111]
	ds_read2_b64 v[238:241], v225 offset0:12 offset1:14
	s_nop 8
	v_max_f32_e32 v0, v81, v81
	v_max_f32_e32 v2, v80, v80
	v_max_f32_e32 v0, v2, v0
	v_max3_f32 v0, v0, v82, v83
	v_max3_f32 v0, v0, v84, v85
	v_max3_f32 v0, v0, v86, v87
	v_max3_f32 v0, v0, v88, v89
	v_max3_f32 v0, v0, v90, v91
	v_max3_f32 v0, v0, v92, v93
	v_max3_f32 v0, v0, v94, v95
	v_max3_f32 v0, v0, v96, v97
	v_max3_f32 v0, v0, v98, v99
	v_max3_f32 v0, v0, v100, v101
	v_max3_f32 v0, v0, v102, v103
	v_max3_f32 v0, v0, v104, v105
	v_max3_f32 v0, v0, v106, v107
	v_max3_f32 v0, v0, v108, v109
	v_max3_f32 v0, v0, v110, v111
	v_mov_b32_e32 v2, v0
	s_nop 1
	v_permlane32_swap_b32_e32 v0, v2
	v_max3_f32 v15, v224, v0, v2
	v_sub_f32_e32 v2, v15, v224
	v_cmp_lt_f32_e32 vcc, 0x41000000, v2
	v_cndmask_b32_e32 v15, v224, v15, vcc
	v_sub_f32_e32 v0, v224, v15
	v_exp_f32_e32 v0, v0
	v_cmp_neq_f32_e32 vcc, v15, v224
	s_cbranch_vccz .LBB0_1912
	v_pk_mul_f32 v[46:47], v[46:47], v[0:1] op_sel_hi:[1,0]
	v_pk_mul_f32 v[44:45], v[44:45], v[0:1] op_sel_hi:[1,0]
	v_pk_mul_f32 v[42:43], v[42:43], v[0:1] op_sel_hi:[1,0]
	v_pk_mul_f32 v[40:41], v[40:41], v[0:1] op_sel_hi:[1,0]
	v_pk_mul_f32 v[38:39], v[38:39], v[0:1] op_sel_hi:[1,0]
	v_pk_mul_f32 v[36:37], v[36:37], v[0:1] op_sel_hi:[1,0]
	v_pk_mul_f32 v[34:35], v[34:35], v[0:1] op_sel_hi:[1,0]
	v_pk_mul_f32 v[32:33], v[32:33], v[0:1] op_sel_hi:[1,0]
	v_pk_mul_f32 v[78:79], v[78:79], v[0:1] op_sel_hi:[1,0]
	v_pk_mul_f32 v[76:77], v[76:77], v[0:1] op_sel_hi:[1,0]
	v_pk_mul_f32 v[74:75], v[74:75], v[0:1] op_sel_hi:[1,0]
	v_pk_mul_f32 v[72:73], v[72:73], v[0:1] op_sel_hi:[1,0]
	v_pk_mul_f32 v[70:71], v[70:71], v[0:1] op_sel_hi:[1,0]
	v_pk_mul_f32 v[68:69], v[68:69], v[0:1] op_sel_hi:[1,0]
	v_pk_mul_f32 v[66:67], v[66:67], v[0:1] op_sel_hi:[1,0]
	v_pk_mul_f32 v[64:65], v[64:65], v[0:1] op_sel_hi:[1,0]
	v_pk_mul_f32 v[62:63], v[62:63], v[0:1] op_sel_hi:[1,0]
	v_pk_mul_f32 v[60:61], v[60:61], v[0:1] op_sel_hi:[1,0]
	v_pk_mul_f32 v[58:59], v[58:59], v[0:1] op_sel_hi:[1,0]
	v_pk_mul_f32 v[56:57], v[56:57], v[0:1] op_sel_hi:[1,0]
	v_pk_mul_f32 v[54:55], v[54:55], v[0:1] op_sel_hi:[1,0]
	v_pk_mul_f32 v[52:53], v[52:53], v[0:1] op_sel_hi:[1,0]
	v_pk_mul_f32 v[50:51], v[50:51], v[0:1] op_sel_hi:[1,0]
	v_pk_mul_f32 v[48:49], v[48:49], v[0:1] op_sel_hi:[1,0]
	v_pk_mul_f32 v[30:31], v[30:31], v[0:1] op_sel_hi:[1,0]
	v_pk_mul_f32 v[28:29], v[28:29], v[0:1] op_sel_hi:[1,0]
	v_pk_mul_f32 v[26:27], v[26:27], v[0:1] op_sel_hi:[1,0]
	v_pk_mul_f32 v[24:25], v[24:25], v[0:1] op_sel_hi:[1,0]
	v_pk_mul_f32 v[22:23], v[22:23], v[0:1] op_sel_hi:[1,0]
	v_pk_mul_f32 v[20:21], v[20:21], v[0:1] op_sel_hi:[1,0]
	v_pk_mul_f32 v[18:19], v[18:19], v[0:1] op_sel_hi:[1,0]
	v_pk_mul_f32 v[16:17], v[16:17], v[0:1] op_sel_hi:[1,0]
